# gMLP epilogue: v_permlane16_swap pairs widen the four dwordx2 Y stores into two dwordx4 stores (64B per row), exact waits recounted for 3 stores per unit
# speedup vs baseline: 1.0030x; 1.0030x over previous
.LBB13_804:
	s_add_i32 s37, s37, s38
	s_andn2_b64 vcc, exec, s[26:27]
	s_cmp_eq_u32 s98, 0
	s_cbranch_scc1 .Lgm0_l10
	s_waitcnt vmcnt(12)
	s_branch .Lgm0_ld
.Lgm0_l10:
	s_waitcnt vmcnt(6)

.LBB13_814:
	s_ashr_i32 s28, s41, 3
	s_add_i32 s28, s28, s31
	s_ashr_i32 s29, s28, 31
	s_lshl_b64 s[28:29], s[28:29], 7
	v_lshl_add_u64 v[68:69], s[28:29], 0, v[76:77]
	v_lshlrev_b32_e32 v112, 16, v110
	v_and_b32_e32 v113, 0xffff0000, v110
	v_pk_add_f32 v[56:57], v[88:89], v[56:57] op_sel_hi:[0,1]
	v_lshlrev_b32_e32 v110, 16, v111
	v_and_b32_e32 v111, 0xffff0000, v111
	v_pk_add_f32 v[58:59], v[88:89], v[58:59] op_sel_hi:[0,1]
	v_lshlrev_b64 v[70:71], 12, v[68:69]
	v_pk_mul_f32 v[56:57], v[56:57], v[112:113]
	v_pk_mul_f32 v[58:59], v[58:59], v[110:111]
	v_lshl_add_u64 v[70:71], s[4:5], 0, v[70:71]
	v_pk_mul_f32 v[110:111], v[56:57], v[56:57]
	v_pk_mul_f32 v[112:113], v[58:59], v[58:59]
	v_pk_mul_f32 v[58:59], v[38:39], v[58:59]
	v_pk_mul_f32 v[56:57], v[36:37], v[56:57]
	v_lshl_or_b32 v0, s42, 7, v104
	v_cvt_pk_bf16_f32 v56, v56, v57
	v_cvt_pk_bf16_f32 v57, v58, v59
	v_lshl_add_u64 v[58:59], v[70:71], 0, v[0:1]
	v_mov_b32_e32 v148, v56
	v_mov_b32_e32 v149, v57
	v_mbcnt_lo_u32_b32 v156, -1, 0
	v_mbcnt_hi_u32_b32 v156, -1, v156
	v_lshrrev_b32_e32 v156, 4, v156
	v_and_b32_e32 v156, 1, v156
	v_mul_u32_u24_e32 v156, 24, v156
	v_mov_b32_e32 v157, 0
	v_lshl_add_u64 v[158:159], v[58:59], 0, v[156:157]
	v_lshlrev_b32_e32 v56, 16, v108
	v_and_b32_e32 v57, 0xffff0000, v108
	v_pk_add_f32 v[52:53], v[88:89], v[52:53] op_sel_hi:[0,1]
	v_pk_mul_f32 v[52:53], v[52:53], v[56:57]
	v_lshlrev_b32_e32 v56, 16, v109
	v_and_b32_e32 v57, 0xffff0000, v109
	v_pk_add_f32 v[54:55], v[88:89], v[54:55] op_sel_hi:[0,1]
	v_pk_mul_f32 v[54:55], v[54:55], v[56:57]
	v_pk_mul_f32 v[56:57], v[52:53], v[52:53]
	v_pk_mul_f32 v[52:53], v[40:41], v[52:53]
	v_pk_mul_f32 v[70:71], v[54:55], v[54:55]
	v_pk_mul_f32 v[54:55], v[42:43], v[54:55]
	v_cvt_pk_bf16_f32 v52, v52, v53
	v_add_f32_e32 v56, v56, v57
	v_cvt_pk_bf16_f32 v53, v54, v55
	v_mov_b32_e32 v150, v52
	v_mov_b32_e32 v151, v53
	s_nop 1
	v_permlane16_swap_b32_e32 v148, v150
	v_permlane16_swap_b32_e32 v149, v151
	global_store_dwordx4 v[158:159], v[148:151], off
	v_lshlrev_b32_e32 v52, 16, v106
	v_and_b32_e32 v53, 0xffff0000, v106
	v_pk_add_f32 v[54:55], v[88:89], v[60:61] op_sel_hi:[0,1]
	v_pk_mul_f32 v[52:53], v[54:55], v[52:53]
	v_lshlrev_b32_e32 v54, 16, v107
	v_and_b32_e32 v55, 0xffff0000, v107
	v_pk_add_f32 v[60:61], v[88:89], v[62:63] op_sel_hi:[0,1]
	v_pk_mul_f32 v[54:55], v[60:61], v[54:55]
	v_pk_mul_f32 v[60:61], v[52:53], v[52:53]
	v_pk_mul_f32 v[62:63], v[54:55], v[54:55]
	v_pk_mul_f32 v[52:53], v[44:45], v[52:53]
	v_pk_mul_f32 v[54:55], v[46:47], v[54:55]
	v_cvt_pk_bf16_f32 v52, v52, v53
	v_add_f32_e32 v0, v62, v63
	v_cvt_pk_bf16_f32 v53, v54, v55
	v_add_f32_e32 v60, v60, v61
	v_mov_b32_e32 v152, v52
	v_mov_b32_e32 v153, v53
	v_lshlrev_b32_e32 v52, 16, v2
	v_and_b32_e32 v53, 0xffff0000, v2
	v_pk_add_f32 v[54:55], v[88:89], v[64:65] op_sel_hi:[0,1]
	v_add_f32_e32 v0, v60, v0
	v_add_f32_e32 v60, v70, v71
	v_pk_mul_f32 v[52:53], v[54:55], v[52:53]
	v_lshlrev_b32_e32 v2, 16, v3
	v_and_b32_e32 v3, 0xffff0000, v3
	v_pk_add_f32 v[54:55], v[88:89], v[66:67] op_sel_hi:[0,1]
	v_add_f32_e32 v56, v56, v60
	v_add_f32_e32 v57, v112, v113
	v_add_f32_e32 v60, v110, v111
	v_pk_mul_f32 v[2:3], v[54:55], v[2:3]
	v_add_f32_e32 v57, v60, v57
	v_pk_mul_f32 v[54:55], v[52:53], v[52:53]
	v_pk_mul_f32 v[64:65], v[2:3], v[2:3]
	v_add_f32_e32 v56, v57, v56
	v_add_f32_e32 v0, v0, v56
	v_add_f32_e32 v56, v64, v65
	v_add_f32_e32 v54, v54, v55
	v_add_f32_e32 v54, v54, v56
	v_add_f32_e32 v0, v54, v0
	ds_swizzle_b32 v54, v0 offset:swizzle(SWAP,16)
	v_pk_mul_f32 v[2:3], v[50:51], v[2:3]
	v_pk_mul_f32 v[52:53], v[48:49], v[52:53]
	s_waitcnt lgkmcnt(0)
	v_add_f32_e32 v0, v0, v54
	v_cvt_pk_bf16_f32 v52, v52, v53
	v_cvt_pk_bf16_f32 v53, v2, v3
	v_mov_b32_e32 v2, v0
	s_nop 1
	v_permlane32_swap_b32_e32 v0, v2
	v_mov_b32_e32 v154, v52
	v_mov_b32_e32 v155, v53
	s_nop 1
	v_permlane16_swap_b32_e32 v152, v154
	v_permlane16_swap_b32_e32 v153, v155
	global_store_dwordx4 v[158:159], v[152:155], off offset:64
	s_and_saveexec_b64 s[28:29], s[6:7]
	s_cbranch_execz .LBB13_816
	v_lshlrev_b64 v[52:53], 6, v[68:69]
	v_lshl_add_u64 v[52:53], s[16:17], 0, v[52:53]
	s_lshl_b32 s84, s42, 2
	v_lshl_add_u64 v[52:53], v[52:53], 0, s[84:85]
	v_add_f32_e32 v0, v0, v2
	global_store_dword v[52:53], v0, off

.LBB13_819:
	s_barrier
	s_and_b64 vcc, exec, s[26:27]
	s_cbranch_vccnz .Lgm0_b10
	s_waitcnt vmcnt(12)
	s_branch .Lgm0_bd

.LBB13_832:
	s_ashr_i32 s8, s29, 3
	s_add_i32 s8, s8, s31
	s_ashr_i32 s9, s8, 31
	s_lshl_b64 s[8:9], s[8:9], 7
	v_lshl_add_u64 v[2:3], s[8:9], 0, v[76:77]
	v_lshlrev_b32_e32 v108, 16, v94
	v_and_b32_e32 v109, 0xffff0000, v94
	s_nop 0
	v_pk_add_f32 v[64:65], v[88:89], v[64:65] op_sel_hi:[0,1]
	v_lshlrev_b32_e32 v94, 16, v95
	v_and_b32_e32 v95, 0xffff0000, v95
	v_pk_add_f32 v[66:67], v[88:89], v[66:67] op_sel_hi:[0,1]
	v_lshlrev_b64 v[106:107], 12, v[2:3]
	v_pk_mul_f32 v[64:65], v[64:65], v[108:109]
	v_pk_mul_f32 v[66:67], v[66:67], v[94:95]
	v_lshl_add_u64 v[106:107], s[4:5], 0, v[106:107]
	v_pk_mul_f32 v[94:95], v[64:65], v[64:65]
	v_pk_mul_f32 v[108:109], v[66:67], v[66:67]
	s_nop 0
	v_pk_mul_f32 v[66:67], v[38:39], v[66:67]
	v_pk_mul_f32 v[64:65], v[36:37], v[64:65]
	v_lshl_or_b32 v0, s28, 7, v104
	v_cvt_pk_bf16_f32 v64, v64, v65
	v_cvt_pk_bf16_f32 v65, v66, v67
	v_lshl_add_u64 v[66:67], v[106:107], 0, v[0:1]
	v_mov_b32_e32 v148, v64
	v_mov_b32_e32 v149, v65
	v_mbcnt_lo_u32_b32 v156, -1, 0
	v_mbcnt_hi_u32_b32 v156, -1, v156
	v_lshrrev_b32_e32 v156, 4, v156
	v_and_b32_e32 v156, 1, v156
	v_mul_u32_u24_e32 v156, 24, v156
	v_mov_b32_e32 v157, 0
	v_lshl_add_u64 v[158:159], v[66:67], 0, v[156:157]
	v_lshlrev_b32_e32 v64, 16, v92
	v_and_b32_e32 v65, 0xffff0000, v92
	v_pk_add_f32 v[60:61], v[88:89], v[60:61] op_sel_hi:[0,1]
	v_pk_mul_f32 v[60:61], v[60:61], v[64:65]
	v_lshlrev_b32_e32 v64, 16, v93
	v_and_b32_e32 v65, 0xffff0000, v93
	v_pk_add_f32 v[62:63], v[88:89], v[62:63] op_sel_hi:[0,1]
	v_pk_mul_f32 v[62:63], v[62:63], v[64:65]
	v_pk_mul_f32 v[64:65], v[60:61], v[60:61]
	s_nop 0
	v_pk_mul_f32 v[60:61], v[40:41], v[60:61]
	v_pk_mul_f32 v[92:93], v[62:63], v[62:63]
	v_pk_mul_f32 v[62:63], v[42:43], v[62:63]
	v_cvt_pk_bf16_f32 v60, v60, v61
	v_pk_add_f32 v[56:57], v[88:89], v[56:57] op_sel_hi:[0,1]
	v_cvt_pk_bf16_f32 v61, v62, v63
	v_mov_b32_e32 v150, v60
	v_mov_b32_e32 v151, v61
	s_nop 1
	v_permlane16_swap_b32_e32 v148, v150
	v_permlane16_swap_b32_e32 v149, v151
	global_store_dwordx4 v[158:159], v[148:151], off
	v_lshlrev_b32_e32 v60, 16, v90
	v_and_b32_e32 v61, 0xffff0000, v90
	v_pk_mul_f32 v[56:57], v[56:57], v[60:61]
	v_lshlrev_b32_e32 v60, 16, v91
	v_and_b32_e32 v61, 0xffff0000, v91
	v_pk_add_f32 v[58:59], v[88:89], v[58:59] op_sel_hi:[0,1]
	v_pk_mul_f32 v[58:59], v[58:59], v[60:61]
	v_pk_mul_f32 v[60:61], v[56:57], v[56:57]
	s_nop 0
	v_pk_mul_f32 v[56:57], v[44:45], v[56:57]
	v_pk_mul_f32 v[62:63], v[58:59], v[58:59]
	v_pk_mul_f32 v[58:59], v[46:47], v[58:59]
	v_cvt_pk_bf16_f32 v56, v56, v57
	v_pk_add_f32 v[52:53], v[88:89], v[52:53] op_sel_hi:[0,1]
	v_cvt_pk_bf16_f32 v57, v58, v59
	v_mov_b32_e32 v152, v56
	v_mov_b32_e32 v153, v57
	v_lshlrev_b32_e32 v56, 16, v86
	v_and_b32_e32 v57, 0xffff0000, v86
	v_pk_mul_f32 v[52:53], v[52:53], v[56:57]
	v_lshlrev_b32_e32 v56, 16, v87
	v_and_b32_e32 v57, 0xffff0000, v87
	v_pk_add_f32 v[54:55], v[88:89], v[54:55] op_sel_hi:[0,1]
	v_add_f32_e32 v0, v108, v109
	v_add_f32_e32 v86, v94, v95
	v_pk_mul_f32 v[54:55], v[54:55], v[56:57]
	v_add_f32_e32 v0, v86, v0
	v_add_f32_e32 v86, v92, v93
	v_add_f32_e32 v64, v64, v65
	v_pk_mul_f32 v[56:57], v[52:53], v[52:53]
	v_pk_mul_f32 v[58:59], v[54:55], v[54:55]
	v_add_f32_e32 v64, v64, v86
	v_add_f32_e32 v62, v62, v63
	v_add_f32_e32 v60, v60, v61
	v_add_f32_e32 v0, v64, v0
	v_add_f32_e32 v60, v60, v62
	v_add_f32_e32 v58, v58, v59
	v_add_f32_e32 v56, v56, v57
	v_add_f32_e32 v0, v60, v0
	v_add_f32_e32 v56, v56, v58
	v_add_f32_e32 v0, v56, v0
	ds_swizzle_b32 v56, v0 offset:swizzle(SWAP,16)
	s_nop 0
	v_pk_mul_f32 v[52:53], v[48:49], v[52:53]
	v_pk_mul_f32 v[54:55], v[50:51], v[54:55]
	v_cvt_pk_bf16_f32 v52, v52, v53
	s_waitcnt lgkmcnt(0)
	v_add_f32_e32 v0, v0, v56
	v_cvt_pk_bf16_f32 v53, v54, v55
	v_mov_b32_e32 v154, v52
	v_mov_b32_e32 v155, v53
	s_nop 1
	v_permlane16_swap_b32_e32 v152, v154
	v_permlane16_swap_b32_e32 v153, v155
	global_store_dwordx4 v[158:159], v[152:155], off offset:64
	v_mov_b32_e32 v52, v0
	s_nop 1
	v_permlane32_swap_b32_e32 v0, v52
	s_and_saveexec_b64 s[8:9], s[6:7]
	s_cbranch_execz .LBB13_803
	v_lshlrev_b64 v[2:3], 6, v[2:3]
	v_lshl_add_u64 v[2:3], s[16:17], 0, v[2:3]
	s_lshl_b32 s84, s28, 2
	v_lshl_add_u64 v[2:3], v[2:3], 0, s[84:85]
	v_add_f32_e32 v0, v0, v52
	global_store_dword v[2:3], v0, off
	s_branch .LBB13_803

.LBB13_1792:
	s_ashr_i32 s28, s41, 3
	s_add_i32 s28, s28, s31
	s_ashr_i32 s29, s28, 31
	s_lshl_b64 s[28:29], s[28:29], 7
	v_lshl_add_u64 v[68:69], s[28:29], 0, v[76:77]
	v_lshlrev_b32_e32 v112, 16, v110
	v_and_b32_e32 v113, 0xffff0000, v110
	v_pk_add_f32 v[56:57], v[88:89], v[56:57] op_sel_hi:[0,1]
	v_lshlrev_b32_e32 v110, 16, v111
	v_and_b32_e32 v111, 0xffff0000, v111
	v_pk_add_f32 v[58:59], v[88:89], v[58:59] op_sel_hi:[0,1]
	v_lshlrev_b64 v[70:71], 12, v[68:69]
	v_pk_mul_f32 v[56:57], v[56:57], v[112:113]
	v_pk_mul_f32 v[58:59], v[58:59], v[110:111]
	v_lshl_add_u64 v[70:71], s[2:3], 0, v[70:71]
	v_pk_mul_f32 v[110:111], v[56:57], v[56:57]
	v_pk_mul_f32 v[112:113], v[58:59], v[58:59]
	v_pk_mul_f32 v[58:59], v[38:39], v[58:59]
	v_pk_mul_f32 v[56:57], v[36:37], v[56:57]
	v_lshl_or_b32 v0, s42, 7, v104
	v_cvt_pk_bf16_f32 v56, v56, v57
	v_cvt_pk_bf16_f32 v57, v58, v59
	v_lshl_add_u64 v[58:59], v[70:71], 0, v[0:1]
	v_mov_b32_e32 v148, v56
	v_mov_b32_e32 v149, v57
	v_mbcnt_lo_u32_b32 v156, -1, 0
	v_mbcnt_hi_u32_b32 v156, -1, v156
	v_lshrrev_b32_e32 v156, 4, v156
	v_and_b32_e32 v156, 1, v156
	v_mul_u32_u24_e32 v156, 24, v156
	v_mov_b32_e32 v157, 0
	v_lshl_add_u64 v[158:159], v[58:59], 0, v[156:157]
	v_lshlrev_b32_e32 v56, 16, v108
	v_and_b32_e32 v57, 0xffff0000, v108
	v_pk_add_f32 v[52:53], v[88:89], v[52:53] op_sel_hi:[0,1]
	v_pk_mul_f32 v[52:53], v[52:53], v[56:57]
	v_lshlrev_b32_e32 v56, 16, v109
	v_and_b32_e32 v57, 0xffff0000, v109
	v_pk_add_f32 v[54:55], v[88:89], v[54:55] op_sel_hi:[0,1]
	v_pk_mul_f32 v[54:55], v[54:55], v[56:57]
	v_pk_mul_f32 v[56:57], v[52:53], v[52:53]
	v_pk_mul_f32 v[52:53], v[40:41], v[52:53]
	v_pk_mul_f32 v[70:71], v[54:55], v[54:55]
	v_pk_mul_f32 v[54:55], v[42:43], v[54:55]
	v_cvt_pk_bf16_f32 v52, v52, v53
	v_add_f32_e32 v56, v56, v57
	v_cvt_pk_bf16_f32 v53, v54, v55
	v_mov_b32_e32 v150, v52
	v_mov_b32_e32 v151, v53
	s_nop 1
	v_permlane16_swap_b32_e32 v148, v150
	v_permlane16_swap_b32_e32 v149, v151
	global_store_dwordx4 v[158:159], v[148:151], off
	v_lshlrev_b32_e32 v52, 16, v106
	v_and_b32_e32 v53, 0xffff0000, v106
	v_pk_add_f32 v[54:55], v[88:89], v[60:61] op_sel_hi:[0,1]
	v_pk_mul_f32 v[52:53], v[54:55], v[52:53]
	v_lshlrev_b32_e32 v54, 16, v107
	v_and_b32_e32 v55, 0xffff0000, v107
	v_pk_add_f32 v[60:61], v[88:89], v[62:63] op_sel_hi:[0,1]
	v_pk_mul_f32 v[54:55], v[60:61], v[54:55]
	v_pk_mul_f32 v[60:61], v[52:53], v[52:53]
	v_pk_mul_f32 v[62:63], v[54:55], v[54:55]
	v_pk_mul_f32 v[52:53], v[44:45], v[52:53]
	v_pk_mul_f32 v[54:55], v[46:47], v[54:55]
	v_cvt_pk_bf16_f32 v52, v52, v53
	v_add_f32_e32 v0, v62, v63
	v_cvt_pk_bf16_f32 v53, v54, v55
	v_add_f32_e32 v60, v60, v61
	v_mov_b32_e32 v152, v52
	v_mov_b32_e32 v153, v53
	v_lshlrev_b32_e32 v52, 16, v2
	v_and_b32_e32 v53, 0xffff0000, v2
	v_pk_add_f32 v[54:55], v[88:89], v[64:65] op_sel_hi:[0,1]
	v_add_f32_e32 v0, v60, v0
	v_add_f32_e32 v60, v70, v71
	v_pk_mul_f32 v[52:53], v[54:55], v[52:53]
	v_lshlrev_b32_e32 v2, 16, v3
	v_and_b32_e32 v3, 0xffff0000, v3
	v_pk_add_f32 v[54:55], v[88:89], v[66:67] op_sel_hi:[0,1]
	v_add_f32_e32 v56, v56, v60
	v_add_f32_e32 v57, v112, v113
	v_add_f32_e32 v60, v110, v111
	v_pk_mul_f32 v[2:3], v[54:55], v[2:3]
	v_add_f32_e32 v57, v60, v57
	v_pk_mul_f32 v[54:55], v[52:53], v[52:53]
	v_pk_mul_f32 v[64:65], v[2:3], v[2:3]
	v_add_f32_e32 v56, v57, v56
	v_add_f32_e32 v0, v0, v56
	v_add_f32_e32 v56, v64, v65
	v_add_f32_e32 v54, v54, v55
	v_add_f32_e32 v54, v54, v56
	v_add_f32_e32 v0, v54, v0
	ds_swizzle_b32 v54, v0 offset:swizzle(SWAP,16)
	v_pk_mul_f32 v[2:3], v[50:51], v[2:3]
	v_pk_mul_f32 v[52:53], v[48:49], v[52:53]
	s_waitcnt lgkmcnt(0)
	v_add_f32_e32 v0, v0, v54
	v_cvt_pk_bf16_f32 v52, v52, v53
	v_cvt_pk_bf16_f32 v53, v2, v3
	v_mov_b32_e32 v2, v0
	s_nop 1
	v_permlane32_swap_b32_e32 v0, v2
	v_mov_b32_e32 v154, v52
	v_mov_b32_e32 v155, v53
	s_nop 1
	v_permlane16_swap_b32_e32 v152, v154
	v_permlane16_swap_b32_e32 v153, v155
	global_store_dwordx4 v[158:159], v[152:155], off offset:64
	s_and_saveexec_b64 s[28:29], s[6:7]
	s_cbranch_execz .LBB13_1794
	v_lshlrev_b64 v[52:53], 6, v[68:69]
	v_lshl_add_u64 v[52:53], s[16:17], 0, v[52:53]
	s_lshl_b32 s84, s42, 2
	v_lshl_add_u64 v[52:53], v[52:53], 0, s[84:85]
	v_add_f32_e32 v0, v0, v2
	global_store_dword v[52:53], v0, off

.LBB13_1810:
	s_ashr_i32 s8, s29, 3
	s_add_i32 s8, s8, s31
	s_ashr_i32 s9, s8, 31
	s_lshl_b64 s[8:9], s[8:9], 7
	v_lshl_add_u64 v[2:3], s[8:9], 0, v[76:77]
	v_lshlrev_b32_e32 v108, 16, v94
	v_and_b32_e32 v109, 0xffff0000, v94
	s_nop 0
	v_pk_add_f32 v[64:65], v[88:89], v[64:65] op_sel_hi:[0,1]
	v_lshlrev_b32_e32 v94, 16, v95
	v_and_b32_e32 v95, 0xffff0000, v95
	v_pk_add_f32 v[66:67], v[88:89], v[66:67] op_sel_hi:[0,1]
	v_lshlrev_b64 v[106:107], 12, v[2:3]
	v_pk_mul_f32 v[64:65], v[64:65], v[108:109]
	v_pk_mul_f32 v[66:67], v[66:67], v[94:95]
	v_lshl_add_u64 v[106:107], s[2:3], 0, v[106:107]
	v_pk_mul_f32 v[94:95], v[64:65], v[64:65]
	v_pk_mul_f32 v[108:109], v[66:67], v[66:67]
	s_nop 0
	v_pk_mul_f32 v[66:67], v[38:39], v[66:67]
	v_pk_mul_f32 v[64:65], v[36:37], v[64:65]
	v_lshl_or_b32 v0, s28, 7, v104
	v_cvt_pk_bf16_f32 v64, v64, v65
	v_cvt_pk_bf16_f32 v65, v66, v67
	v_lshl_add_u64 v[66:67], v[106:107], 0, v[0:1]
	v_mov_b32_e32 v148, v64
	v_mov_b32_e32 v149, v65
	v_mbcnt_lo_u32_b32 v156, -1, 0
	v_mbcnt_hi_u32_b32 v156, -1, v156
	v_lshrrev_b32_e32 v156, 4, v156
	v_and_b32_e32 v156, 1, v156
	v_mul_u32_u24_e32 v156, 24, v156
	v_mov_b32_e32 v157, 0
	v_lshl_add_u64 v[158:159], v[66:67], 0, v[156:157]
	v_lshlrev_b32_e32 v64, 16, v92
	v_and_b32_e32 v65, 0xffff0000, v92
	v_pk_add_f32 v[60:61], v[88:89], v[60:61] op_sel_hi:[0,1]
	v_pk_mul_f32 v[60:61], v[60:61], v[64:65]
	v_lshlrev_b32_e32 v64, 16, v93
	v_and_b32_e32 v65, 0xffff0000, v93
	v_pk_add_f32 v[62:63], v[88:89], v[62:63] op_sel_hi:[0,1]
	v_pk_mul_f32 v[62:63], v[62:63], v[64:65]
	v_pk_mul_f32 v[64:65], v[60:61], v[60:61]
	s_nop 0
	v_pk_mul_f32 v[60:61], v[40:41], v[60:61]
	v_pk_mul_f32 v[92:93], v[62:63], v[62:63]
	v_pk_mul_f32 v[62:63], v[42:43], v[62:63]
	v_cvt_pk_bf16_f32 v60, v60, v61
	v_pk_add_f32 v[56:57], v[88:89], v[56:57] op_sel_hi:[0,1]
	v_cvt_pk_bf16_f32 v61, v62, v63
	v_mov_b32_e32 v150, v60
	v_mov_b32_e32 v151, v61
	s_nop 1
	v_permlane16_swap_b32_e32 v148, v150
	v_permlane16_swap_b32_e32 v149, v151
	global_store_dwordx4 v[158:159], v[148:151], off
	v_lshlrev_b32_e32 v60, 16, v90
	v_and_b32_e32 v61, 0xffff0000, v90
	v_pk_mul_f32 v[56:57], v[56:57], v[60:61]
	v_lshlrev_b32_e32 v60, 16, v91
	v_and_b32_e32 v61, 0xffff0000, v91
	v_pk_add_f32 v[58:59], v[88:89], v[58:59] op_sel_hi:[0,1]
	v_pk_mul_f32 v[58:59], v[58:59], v[60:61]
	v_pk_mul_f32 v[60:61], v[56:57], v[56:57]
	s_nop 0
	v_pk_mul_f32 v[56:57], v[44:45], v[56:57]
	v_pk_mul_f32 v[62:63], v[58:59], v[58:59]
	v_pk_mul_f32 v[58:59], v[46:47], v[58:59]
	v_cvt_pk_bf16_f32 v56, v56, v57
	v_pk_add_f32 v[52:53], v[88:89], v[52:53] op_sel_hi:[0,1]
	v_cvt_pk_bf16_f32 v57, v58, v59
	v_mov_b32_e32 v152, v56
	v_mov_b32_e32 v153, v57
	v_lshlrev_b32_e32 v56, 16, v86
	v_and_b32_e32 v57, 0xffff0000, v86
	v_pk_mul_f32 v[52:53], v[52:53], v[56:57]
	v_lshlrev_b32_e32 v56, 16, v87
	v_and_b32_e32 v57, 0xffff0000, v87
	v_pk_add_f32 v[54:55], v[88:89], v[54:55] op_sel_hi:[0,1]
	v_add_f32_e32 v0, v108, v109
	v_add_f32_e32 v86, v94, v95
	v_pk_mul_f32 v[54:55], v[54:55], v[56:57]
	v_add_f32_e32 v0, v86, v0
	v_add_f32_e32 v86, v92, v93
	v_add_f32_e32 v64, v64, v65
	v_pk_mul_f32 v[56:57], v[52:53], v[52:53]
	v_pk_mul_f32 v[58:59], v[54:55], v[54:55]
	v_add_f32_e32 v64, v64, v86
	v_add_f32_e32 v62, v62, v63
	v_add_f32_e32 v60, v60, v61
	v_add_f32_e32 v0, v64, v0
	v_add_f32_e32 v60, v60, v62
	v_add_f32_e32 v58, v58, v59
	v_add_f32_e32 v56, v56, v57
	v_add_f32_e32 v0, v60, v0
	v_add_f32_e32 v56, v56, v58
	v_add_f32_e32 v0, v56, v0
	ds_swizzle_b32 v56, v0 offset:swizzle(SWAP,16)
	s_nop 0
	v_pk_mul_f32 v[52:53], v[48:49], v[52:53]
	v_pk_mul_f32 v[54:55], v[50:51], v[54:55]
	v_cvt_pk_bf16_f32 v52, v52, v53
	s_waitcnt lgkmcnt(0)
	v_add_f32_e32 v0, v0, v56
	v_cvt_pk_bf16_f32 v53, v54, v55
	v_mov_b32_e32 v154, v52
	v_mov_b32_e32 v155, v53
	s_nop 1
	v_permlane16_swap_b32_e32 v152, v154
	v_permlane16_swap_b32_e32 v153, v155
	global_store_dwordx4 v[158:159], v[152:155], off offset:64
	v_mov_b32_e32 v52, v0
	s_nop 1
	v_permlane32_swap_b32_e32 v0, v52
	s_and_saveexec_b64 s[8:9], s[6:7]
	s_cbranch_execz .LBB13_1781
	v_lshlrev_b64 v[2:3], 6, v[2:3]
	v_lshl_add_u64 v[2:3], s[16:17], 0, v[2:3]
	s_lshl_b32 s84, s28, 2
	v_lshl_add_u64 v[2:3], v[2:3], 0, s[84:85]
	v_add_f32_e32 v0, v0, v52
	global_store_dword v[2:3], v0, off
	s_branch .LBB13_1781
